# H-phase: next tile's first 14 LDS-DMA loads issued before the epilogue (cross-tile prefetch), prologue waits/barriers removed
# baseline (speedup 1.0000x reference)
; #define WAIT_V(n) asm volatile("s_waitcnt vmcnt(" #n ")" ::: "memory")
; #define BAR __builtin_amdgcn_s_barrier()
; DI void gemm256(int wv0, f32x4 (&acc)[2][2][4][2], const u16* __restrict__ A, int lda, const u16* __restrict__ Bt, int ldb,
;                 int K, unsigned char* smem) {
;     ...
;   stage_rc(tid * 16, sr0, sc0);
;   stage_rc(tid * 16 + 8192, sr1, sc1);
;   const u16* a0 = A + (size_t)sr0 * lda + sc0;
;   const u16* a1 = A + (size_t)sr1 * lda + sc1;
;   const u16* b0 = Bt + (size_t)sr0 * ldb + sc0;
;   const u16* b1 = Bt + (size_t)sr1 * ldb + sc1;
;     ...
; #pragma unroll
;   for (int a = 0; a < 2; ++a)
; #pragma unroll
;     for (int b = 0; b < 2; ++b)
; #pragma unroll
;       for (int m = 0; m < 4; ++m)
; #pragma unroll
;         for (int n = 0; n < 2; ++n) acc[a][b][m][n] = f32x4{0.f, 0.f, 0.f, 0.f};
;   bf16x8 At[4][2], B0[2][2], B1[2][2];
;   const int nt = K / 64;
;   WAIT_V(0);
;   __syncthreads();
;   STAGE_B(SB(0, 0), 0, 0) STAGE_A(SA(0, 0), 0, 0)
;   STAGE_B(SB(0, 1), 1, 0) STAGE_A(SA(0, 1), 1, 0)
;   if (wr == 1) BAR;
;   WAIT_V(4); BAR;
;   STAGE_B(SB(1, 0), 0, 1) STAGE_A(SA(1, 0), 0, 1) STAGE_B(SB(1, 1), 1, 1)
; DI void phaseH(int wv0, PP p, unsigned char* smem) {
;   const u16* X1B = (const u16*)(p->ws + OFF_X1B);
;   const float* SS1 = (const float*)(p->ws + OFF_SS1);
;   u16* ACT = (u16*)(p->ws + OFF_ACT);
;   float* sR = (float*)(smem + 131072);
;   for (int id = blockIdx.x; id < 128 * 16; id += gridDim.x) {
;     int pm, pn;
;     tile_map_n16(id, pm, pn);
;     const int brow = pm * 256, bcol = pn * 256;
.LBB0_1131:
	s_cmpk_gt_i32 s94, 0x7ff
	s_cbranch_scc1 .LBB0_1142
	s_load_dwordx2 s[2:3], s[4:5], 0xc8
	v_mbcnt_lo_u32_b32 v0, -1, 0
	v_mbcnt_hi_u32_b32 v0, -1, v0
	s_mov_b32 s5, 0
	s_movk_i32 s55, 0x100
	s_waitcnt lgkmcnt(0)
	s_add_u32 s0, s2, 0x133d4100
	s_addc_u32 s1, s3, 0
	s_add_u32 s8, s2, 0x1fd4100
	s_addc_u32 s9, s3, 0
	s_add_u32 s10, s2, 0x33d4100
	s_addc_u32 s11, s3, 0
	s_and_b32 s4, s82, 0xffffffc0
	s_add_u32 s33, s2, 0xf40000
	v_add_u32_e32 v142, s4, v0
	s_addc_u32 s50, s3, 0
	s_lshr_b32 s4, s82, 8
	s_cmp_eq_u32 s4, 1
	s_cselect_b64 s[12:13], -1, 0
	s_lshl_b32 s51, s4, 6
	s_lshl_b32 s14, s89, 12
	s_or_b32 s52, s51, 16
	s_or_b32 s53, s51, 32
	s_or_b32 s54, s51, 48
	s_and_b32 s18, s14, 0x3000
	s_lshl_b32 s4, s4, 13
	s_lshl_b32 s19, s52, 7
	s_lshl_b32 s20, s53, 7
	s_lshl_b32 s21, s54, 7
	s_cmpk_lt_u32 s82, 0x100
	s_cselect_b64 s[14:15], -1, 0
	s_lshl_b32 s16, s89, 4
	s_and_b32 s56, s16, 0x3fffffc0
	s_lshl_b32 s16, s89, 5
	s_and_b32 s57, s16, 0x60
	s_add_u32 s16, s90, 0xd8
	s_addc_u32 s17, s91, 0
	s_add_i32 s65, s18, 32
	s_add_i32 s58, s65, 0x10000
	s_add_i32 s59, s4, 32
	s_add_i32 s60, s19, 32
	s_add_i32 s61, s20, 32
	s_add_i32 s62, s21, 32
	s_add_i32 s63, s65, 0x14000
	s_add_i32 s64, s65, 0x18000
	s_add_i32 s65, s65, 0x1c000
	v_mov_b32_e32 v143, 0x358637bd
	s_mov_b32 s66, 0x800000
	s_mov_b64 s[18:19], 0x40000
	s_mov_b64 s[20:21], 0x80
	s_mov_b64 s[22:23], 0x40080
	s_mov_b64 s[24:25], 0x13414180
	s_mov_b64 s[26:27], 0xf40100
	s_mov_b64 s[28:29], 0x133d4200
	s_mov_b64 s[30:31], 0xf80100
	s_mov_b64 s[34:35], 0x13414200
	s_mov_b64 s[36:37], 0xf40180
	s_mov_b64 s[38:39], 0x133d4280
	s_mov_b64 s[40:41], 0xf80180
	s_mov_b64 s[42:43], 0x100
	s_mov_b64 s[44:45], 0x40780
	v_mov_b32_e32 v129, 0
	v_mov_b32_e32 v144, 1
	s_load_dword s32, s[16:17], 0x0
	s_lshl_b32 s86, s82, 4
	v_and_b32_e32 v248, 63, v142
	v_lshlrev_b32_e32 v249, 4, v248
	v_and_b32_e32 v250, 32, v248
	v_xor_b32_e32 v249, v249, v250
	v_lshrrev_b32_e32 v250, 6, v249
	s_lshr_b32 s87, s89, 1
	s_lshl_b32 s87, s87, 4
	v_add_u32_e32 v250, s87, v250
	v_and_b32_e32 v249, 63, v249
	v_lshrrev_b32_e32 v249, 1, v249
	s_and_b32 s87, s89, 1
	s_lshl_b32 s87, s87, 5
	v_add_u32_e32 v249, s87, v249
	v_lshlrev_b32_e32 v250, 11, v250
	v_lshl_add_u32 v248, v249, 1, v250
	v_add_u32_e32 v249, 0x20000, v248
	v_add_u32_e32 v250, 0x40000, v248
	v_add_u32_e32 v251, 0x60000, v248
	v_add_u32_e32 v252, 0x80, v248
	v_add_u32_e32 v253, 0x20080, v248
	v_add_u32_e32 v254, 0x40080, v248
	v_add_u32_e32 v255, 0x60080, v248
	s_waitcnt lgkmcnt(0)
	s_ashr_i32 s79, s94, 4
	s_and_b32 s79, s79, -16
	s_lshl_b32 s83, s94, 1
	s_and_b32 s83, s83, 12
	s_or_b32 s79, s79, s83
	s_bfe_u32 s83, s94, 0x20006
	s_or_b32 s79, s79, s83
	s_lshl_b32 s80, s79, 8
	s_ashr_i32 s81, s80, 31
	s_lshl_b64 s[80:81], s[80:81], 11
	s_add_u32 s80, s0, s80
	s_addc_u32 s81, s1, s81
	s_lshl_b32 s83, s94, 3
	s_and_b32 s83, s83, 8
	s_bfe_u32 s79, s94, 0x30003
	s_or_b32 s83, s83, s79
	s_lshl_b32 s83, s83, 19
	s_add_u32 s84, s33, s83
	s_addc_u32 s85, s50, 0
	s_add_i32 m0, s86, 0x10020
	s_nop 0
	global_load_lds_dwordx4 v248, s[84:85]
	s_add_i32 m0, s86, 0x12020
	s_nop 0
	global_load_lds_dwordx4 v249, s[84:85]
	s_add_i32 m0, s86, 0x20
	s_nop 0
	global_load_lds_dwordx4 v248, s[80:81]
	s_add_i32 m0, s86, 0x2020
	s_nop 0
	global_load_lds_dwordx4 v249, s[80:81]
	s_add_i32 m0, s86, 0x14020
	s_nop 0
	global_load_lds_dwordx4 v250, s[84:85]
	s_add_i32 m0, s86, 0x16020
	s_nop 0
	global_load_lds_dwordx4 v251, s[84:85]
	s_add_i32 m0, s86, 0x4020
	s_nop 0
	global_load_lds_dwordx4 v250, s[80:81]
	s_add_i32 m0, s86, 0x6020
	s_nop 0
	global_load_lds_dwordx4 v251, s[80:81]
	s_add_i32 m0, s86, 0x18020
	s_nop 0
	global_load_lds_dwordx4 v252, s[84:85]
	s_add_i32 m0, s86, 0x1a020
	s_nop 0
	global_load_lds_dwordx4 v253, s[84:85]
	s_add_i32 m0, s86, 0x8020
	s_nop 0
	global_load_lds_dwordx4 v252, s[80:81]
	s_add_i32 m0, s86, 0xa020
	s_nop 0
	global_load_lds_dwordx4 v253, s[80:81]
	s_add_i32 m0, s86, 0x1c020
	s_nop 0
	global_load_lds_dwordx4 v254, s[84:85]
	s_add_i32 m0, s86, 0x1e020
	s_nop 0
	global_load_lds_dwordx4 v255, s[84:85]
	s_mov_b32 s67, s94
	s_branch .LBB0_1134
.LBB0_1133:
	s_add_i32 s78, s67, s32
	s_cmpk_lt_i32 s78, 0x800
	s_cbranch_scc0 .Lmy_H_nopf
	s_ashr_i32 s79, s78, 4
	s_and_b32 s79, s79, -16
	s_lshl_b32 s83, s78, 1
	s_and_b32 s83, s83, 12
	s_or_b32 s79, s79, s83
	s_bfe_u32 s83, s78, 0x20006
	s_or_b32 s79, s79, s83
	s_lshl_b32 s80, s79, 8
	s_ashr_i32 s81, s80, 31
	s_lshl_b64 s[80:81], s[80:81], 11
	s_add_u32 s80, s0, s80
	s_addc_u32 s81, s1, s81
	s_lshl_b32 s83, s78, 3
	s_and_b32 s83, s83, 8
	s_bfe_u32 s79, s78, 0x30003
	s_or_b32 s83, s83, s79
	s_lshl_b32 s83, s83, 19
	s_add_u32 s84, s33, s83
	s_addc_u32 s85, s50, 0
	s_add_i32 m0, s86, 0x10020
	s_nop 0
	global_load_lds_dwordx4 v248, s[84:85]
	s_add_i32 m0, s86, 0x12020
	s_nop 0
	global_load_lds_dwordx4 v249, s[84:85]
	s_add_i32 m0, s86, 0x20
	s_nop 0
	global_load_lds_dwordx4 v248, s[80:81]
	s_add_i32 m0, s86, 0x2020
	s_nop 0
	global_load_lds_dwordx4 v249, s[80:81]
	s_add_i32 m0, s86, 0x14020
	s_nop 0
	global_load_lds_dwordx4 v250, s[84:85]
	s_add_i32 m0, s86, 0x16020
	s_nop 0
	global_load_lds_dwordx4 v251, s[84:85]
	s_add_i32 m0, s86, 0x4020
	s_nop 0
	global_load_lds_dwordx4 v250, s[80:81]
	s_add_i32 m0, s86, 0x6020
	s_nop 0
	global_load_lds_dwordx4 v251, s[80:81]
	s_add_i32 m0, s86, 0x18020
	s_nop 0
	global_load_lds_dwordx4 v252, s[84:85]
	s_add_i32 m0, s86, 0x1a020
	s_nop 0
	global_load_lds_dwordx4 v253, s[84:85]
	s_add_i32 m0, s86, 0x8020
	s_nop 0
	global_load_lds_dwordx4 v252, s[80:81]
	s_add_i32 m0, s86, 0xa020
	s_nop 0
	global_load_lds_dwordx4 v253, s[80:81]
	s_add_i32 m0, s86, 0x1c020
	s_nop 0
	global_load_lds_dwordx4 v254, s[84:85]
	s_add_i32 m0, s86, 0x1e020
	s_nop 0
	global_load_lds_dwordx4 v255, s[84:85]

; #define WAIT_V(n) asm volatile("s_waitcnt vmcnt(" #n ")" ::: "memory")
; #define BAR __builtin_amdgcn_s_barrier()
; DI void gemm256(int wv0, f32x4 (&acc)[2][2][4][2], const u16* __restrict__ A, int lda, const u16* __restrict__ Bt, int ldb,
;                 int K, unsigned char* smem) {
;   u16* shm = (u16*)smem;
;   const int tid = my_tid(wv0), lane = tid & 63;
;   const int wr = wv0 >> 2, wc = wv0 & 3, fr = lane & 15, fq = lane >> 4;
;     ...
;   int sr0, sc0, sr1, sc1;
;   stage_rc(tid * 16, sr0, sc0);
;   stage_rc(tid * 16 + 8192, sr1, sc1);
;   const u16* a0 = A + (size_t)sr0 * lda + sc0;
;   const u16* a1 = A + (size_t)sr1 * lda + sc1;
;   const u16* b0 = Bt + (size_t)sr0 * ldb + sc0;
;   const u16* b1 = Bt + (size_t)sr1 * ldb + sc1;
;     ...
;   STAGE_B(SB(0, 0), 0, 0) STAGE_A(SA(0, 0), 0, 0)
;   STAGE_B(SB(0, 1), 1, 0) STAGE_A(SA(0, 1), 1, 0)
;   if (wr == 1) BAR;
;   WAIT_V(4); BAR;
.LBB0_1136:
	s_or_b64 exec, exec, s[48:49]
	v_mov_b32_e32 v12, v142
	s_lshl_b32 s4, s67, 3
	v_bfe_i32 v1, v12, 27, 1
	v_lshlrev_b32_e32 v13, 4, v12
	v_lshrrev_b32_e32 v1, 22, v1
	v_add_u32_e32 v1, v13, v1
	v_and_b32_e32 v1, 0xfffffc00, v1
	v_ashrrev_i32_e32 v0, 31, v12
	v_sub_u32_e32 v1, v13, v1
	v_lshrrev_b32_e32 v0, 26, v0
	v_lshrrev_b32_e32 v2, 4, v1
	v_add_u32_e32 v0, v12, v0
	v_bitop3_b32 v2, v2, v1, 32 bitop3:0x6c
	v_ashrrev_i32_e32 v1, 31, v1
	v_ashrrev_i32_e32 v0, 6, v0
	v_lshrrev_b32_e32 v1, 26, v1
	v_lshlrev_b32_e32 v3, 3, v0
	v_add_u32_e32 v1, v2, v1
	v_and_b32_e32 v3, -16, v3
	v_ashrrev_i32_e32 v1, 6, v1
	v_add_u32_e32 v4, v1, v3
	v_mul_i32_i24_e32 v1, 64, v1
	v_lshlrev_b32_e32 v0, 5, v0
	v_sub_u32_e32 v1, v2, v1
	v_and_b32_e32 v0, 32, v0
	v_ashrrev_i16_sdwa v1, v144, sext(v1) dst_sel:DWORD dst_unused:UNUSED_PAD src0_sel:DWORD src1_sel:BYTE_0
	v_add_u32_sdwa v0, v0, sext(v1) dst_sel:DWORD dst_unused:UNUSED_PAD src0_sel:DWORD src1_sel:WORD_0
	v_add_u32_e32 v1, 0x2000, v13
	v_ashrrev_i32_e32 v2, 31, v1
	v_lshrrev_b32_e32 v2, 22, v2
	v_add_u32_e32 v2, v1, v2
	v_ashrrev_i32_e32 v2, 10, v2
	v_mul_i32_i24_e32 v3, 0x400, v2
	v_sub_u32_e32 v1, v1, v3
	v_lshrrev_b32_e32 v3, 4, v1
	v_bitop3_b32 v1, v3, v1, 32 bitop3:0x6c
	s_and_b32 s47, s4, 8
	s_bfe_u32 s4, s67, 0x30003
	v_ashrrev_i32_e32 v5, 31, v1
	s_or_b32 s48, s47, s4
	s_ashr_i32 s47, s46, 31
	v_lshrrev_b32_e32 v5, 26, v5
	s_lshl_b64 s[72:73], s[46:47], 11
	v_lshlrev_b32_e32 v3, 3, v2
	v_add_u32_e32 v5, v1, v5
	s_add_u32 s72, s0, s72
	v_and_b32_e32 v3, -16, v3
	v_ashrrev_i32_e32 v6, 6, v5
	s_addc_u32 s73, s1, s73
	s_lshl_b32 s47, s48, 19
	v_add_u32_e32 v8, v6, v3
	v_and_b32_e32 v3, 0xc0, v5
	s_add_u32 s74, s33, s47
	v_lshlrev_b32_e32 v2, 5, v2
	v_sub_u32_e32 v1, v1, v3
	s_addc_u32 s75, s50, 0
	v_and_b32_e32 v2, 32, v2
	v_ashrrev_i16_sdwa v1, v144, sext(v1) dst_sel:DWORD dst_unused:UNUSED_PAD src0_sel:DWORD src1_sel:BYTE_0
	v_ashrrev_i32_e32 v5, 31, v4
	s_add_i32 s47, 32, 0x10000
	v_add_u32_sdwa v2, v2, sext(v1) dst_sel:DWORD dst_unused:UNUSED_PAD src0_sel:DWORD src1_sel:WORD_0
	v_ashrrev_i32_e32 v1, 31, v0
	v_ashrrev_i32_e32 v9, 31, v8
	v_lshlrev_b64 v[6:7], 11, v[4:5]
	v_add_u32_e32 v148, s47, v13
	v_ashrrev_i32_e32 v3, 31, v2
	v_lshl_add_u64 v[10:11], s[74:75], 0, v[6:7]
	v_lshlrev_b64 v[4:5], 11, v[8:9]
	v_lshlrev_b64 v[16:17], 1, v[0:1]
	v_readfirstlane_b32 s47, v148
	v_add_u32_e32 v149, 0x2000, v148
	v_lshl_add_u64 v[8:9], s[74:75], 0, v[4:5]
	v_lshlrev_b64 v[18:19], 1, v[2:3]
	v_lshl_add_u64 v[10:11], v[10:11], 0, v[16:17]
	s_mov_b32 m0, s47
	v_readfirstlane_b32 s47, v149
	v_add_u32_e32 v150, 32, v13
	v_lshl_add_u64 v[14:15], s[72:73], 0, v[6:7]
	v_lshl_add_u64 v[8:9], v[8:9], 0, v[18:19]
	s_waitcnt vmcnt(0)
	s_waitcnt vmcnt(0) lgkmcnt(0)
	s_barrier
	s_nop 0
	s_mov_b32 m0, s47
	v_readfirstlane_b32 s47, v150
	v_add_u32_e32 v151, 0x2000, v150
	v_lshl_add_u64 v[132:133], v[14:15], 0, v[16:17]
	s_nop 0
	s_mov_b32 m0, s47
	v_readfirstlane_b32 s47, v151
	s_nop 0
	s_mov_b32 m0, s47
	s_add_i32 s47, 32, 0x14000
	v_lshl_add_u64 v[14:15], s[72:73], 0, v[4:5]
	v_add_u32_e32 v152, s47, v13
	v_lshl_add_u64 v[130:131], v[14:15], 0, v[18:19]
	v_readfirstlane_b32 s47, v152
	v_add_u32_e32 v153, 0x2000, v152
	s_nop 0
	v_lshl_add_u64 v[14:15], v[10:11], 0, s[18:19]
	s_mov_b32 m0, s47
	v_readfirstlane_b32 s47, v153
	v_add_u32_e32 v154, 0x4000, v150
	s_nop 0
	v_lshl_add_u64 v[14:15], v[8:9], 0, s[18:19]
	s_mov_b32 m0, s47
	v_readfirstlane_b32 s47, v154
	v_add_u32_e32 v155, 0x6000, v150
	s_nop 0
	v_lshl_add_u64 v[14:15], v[132:133], 0, s[18:19]
	s_mov_b32 m0, s47
	v_readfirstlane_b32 s47, v155
	s_nop 0
	v_lshl_add_u64 v[14:15], v[130:131], 0, s[18:19]
	s_mov_b32 m0, s47
	s_andn2_b64 vcc, exec, s[12:13]
	s_nop 0
	s_cbranch_vccnz .LBB0_1138
	s_barrier
; #define WAIT_V(n) asm volatile("s_waitcnt vmcnt(" #n ")" ::: "memory")
; #define BAR __builtin_amdgcn_s_barrier()
; DI void gemm256(int wv0, f32x4 (&acc)[2][2][4][2], const u16* __restrict__ A, int lda, const u16* __restrict__ Bt, int ldb,
;                 int K, unsigned char* smem) {
;     ...
; #pragma unroll
;   for (int a = 0; a < 2; ++a)
; #pragma unroll
;     for (int b = 0; b < 2; ++b)
; #pragma unroll
;       for (int m = 0; m < 4; ++m)
; #pragma unroll
;         for (int n = 0; n < 2; ++n) acc[a][b][m][n] = f32x4{0.f, 0.f, 0.f, 0.f};
;     ...
;   WAIT_V(4); BAR;
;   STAGE_B(SB(1, 0), 0, 1) STAGE_A(SA(1, 0), 0, 1) STAGE_B(SB(1, 1), 1, 1)
;   WAIT_V(6); BAR;
.LBB0_1138:
	s_add_i32 s47, 32, 0x18000
	v_add_u32_e32 v156, s47, v13
	v_add_u32_e32 v157, 0x2000, v156
	v_readfirstlane_b32 s47, v156
	v_lshl_add_u64 v[14:15], v[10:11], 0, s[20:21]
	s_mov_b32 m0, s47
	v_readfirstlane_b32 s47, v157
	v_add_u32_e32 v158, 0x8000, v150
	s_nop 0
	s_nop 0
	s_nop 0
	v_lshl_add_u64 v[14:15], v[8:9], 0, s[20:21]
	s_mov_b32 m0, s47
	v_readfirstlane_b32 s47, v158
	v_add_u32_e32 v159, 0xa000, v150
	s_nop 0
	v_lshl_add_u64 v[14:15], v[132:133], 0, s[20:21]
	s_mov_b32 m0, s47
	v_readfirstlane_b32 s47, v159
	s_nop 0
	s_mov_b32 m0, s47
	s_add_i32 s47, 32, 0x1c000
	v_add_u32_e32 v160, s47, v13
	v_lshl_add_u64 v[14:15], v[130:131], 0, s[20:21]
	v_readfirstlane_b32 s47, v160
	v_add_u32_e32 v161, 0x2000, v160
	s_nop 0
	v_lshl_add_u64 v[10:11], v[10:11], 0, s[22:23]
	s_mov_b32 m0, s47
	v_readfirstlane_b32 s47, v161
	s_nop 0
	v_lshl_add_u64 v[8:9], v[8:9], 0, s[22:23]
	s_mov_b32 m0, s47
	v_and_b32_e32 v16, 15, v12
	s_nop 0
	v_lshlrev_b32_e32 v9, 2, v12
	v_and_b32_e32 v17, 48, v12
	v_lshlrev_b32_e32 v8, 6, v16
	v_and_b32_e32 v9, 32, v9
	v_bitop3_b32 v162, v8, v9, v17 bitop3:0x36
	v_or_b32_e32 v8, s51, v16
	v_lshlrev_b32_e32 v9, 6, v8
	v_lshlrev_b32_e32 v8, 2, v8
	v_and_b32_e32 v9, 0x3c0, v9
	v_and_b32_e32 v8, 32, v8
	v_bitop3_b32 v8, v9, v8, v17 bitop3:0x36
	v_or_b32_e32 v9, s52, v16
	v_lshlrev_b32_e32 v10, 6, v9
	v_lshlrev_b32_e32 v9, 2, v9
	s_and_b32 s47, s67, 1
	v_and_b32_e32 v10, 0x3c0, v10
	v_and_b32_e32 v9, 32, v9
	s_lshl_b32 s47, s47, 22
	s_lshl_b32 s4, s4, 19
	v_bitop3_b32 v9, v10, v9, v17 bitop3:0x36
	v_or_b32_e32 v10, s53, v16
	v_lshl_add_u64 v[0:1], v[0:1], 1, v[6:7]
	s_or_b32 s4, s47, s4
	v_lshl_add_u64 v[2:3], v[2:3], 1, v[4:5]
	v_lshlrev_b32_e32 v11, 6, v10
	v_lshlrev_b32_e32 v10, 2, v10
	v_lshl_add_u64 v[134:135], v[0:1], 0, s[4:5]
	v_lshl_add_u64 v[136:137], v[2:3], 0, s[4:5]
	s_add_i32 s4, s68, s69
	v_and_b32_e32 v11, 0x3c0, v11
	v_and_b32_e32 v10, 32, v10
	s_add_i32 s4, s4, s70
	v_bitop3_b32 v10, v11, v10, v17 bitop3:0x36
	v_or_b32_e32 v11, s54, v16
	s_lshl_b32 s68, s4, 8
	v_lshlrev_b32_e32 v12, 6, v11
	v_lshlrev_b32_e32 v11, 2, v11
	s_ashr_i32 s69, s68, 31
	s_nop 0
	v_and_b32_e32 v12, 0x3c0, v12
	v_and_b32_e32 v11, 32, v11
	s_lshl_b64 s[68:69], s[68:69], 11
	v_bitop3_b32 v11, v12, v11, v17 bitop3:0x36
	v_lshl_add_u64 v[138:139], v[0:1], 0, s[68:69]
	v_mov_b32_e32 v0, 0
	v_lshl_add_u64 v[140:141], v[2:3], 0, s[68:69]
	s_mov_b32 s4, -2
	v_add_u32_e32 v147, s59, v8
	v_add_u32_e32 v146, s60, v9
	v_add_u32_e32 v145, s61, v10
	v_add_u32_e32 v128, s62, v11
	v_mov_b32_e32 v1, v0
	v_mov_b32_e32 v2, v0
	v_mov_b32_e32 v3, v0
	v_mov_b32_e32 v4, v0
	v_mov_b32_e32 v5, v0
	v_mov_b32_e32 v6, v0
	v_mov_b32_e32 v7, v0
	v_mov_b32_e32 v8, v0
	v_mov_b32_e32 v9, v0
	v_mov_b32_e32 v10, v0
	v_mov_b32_e32 v11, v0
	v_mov_b32_e32 v12, v0
	v_mov_b32_e32 v13, v0
	v_mov_b32_e32 v14, v0
	v_mov_b32_e32 v15, v0
	v_mov_b32_e32 v16, v0
	v_mov_b32_e32 v17, v0
	v_mov_b32_e32 v18, v0
	v_mov_b32_e32 v19, v0
	v_mov_b32_e32 v20, v0
	v_mov_b32_e32 v21, v0
	v_mov_b32_e32 v22, v0
	v_mov_b32_e32 v23, v0
	v_mov_b32_e32 v24, v0
	v_mov_b32_e32 v25, v0
	v_mov_b32_e32 v26, v0
	v_mov_b32_e32 v27, v0
	v_mov_b32_e32 v28, v0
	v_mov_b32_e32 v29, v0
	v_mov_b32_e32 v30, v0
	v_mov_b32_e32 v31, v0
	v_mov_b32_e32 v32, v0
	v_mov_b32_e32 v33, v0
	v_mov_b32_e32 v34, v0
	v_mov_b32_e32 v35, v0
	v_mov_b32_e32 v36, v0
	v_mov_b32_e32 v37, v0
	v_mov_b32_e32 v38, v0
	v_mov_b32_e32 v39, v0
	v_mov_b32_e32 v40, v0
	v_mov_b32_e32 v41, v0
	v_mov_b32_e32 v42, v0
	v_mov_b32_e32 v43, v0
	v_mov_b32_e32 v44, v0
	v_mov_b32_e32 v45, v0
	v_mov_b32_e32 v46, v0
	v_mov_b32_e32 v47, v0
	v_mov_b32_e32 v48, v0
	v_mov_b32_e32 v49, v0
	v_mov_b32_e32 v50, v0
	v_mov_b32_e32 v51, v0
	v_mov_b32_e32 v52, v0
	v_mov_b32_e32 v53, v0
	v_mov_b32_e32 v54, v0
	v_mov_b32_e32 v55, v0
	v_mov_b32_e32 v56, v0
	v_mov_b32_e32 v57, v0
	v_mov_b32_e32 v58, v0
	v_mov_b32_e32 v59, v0
	v_mov_b32_e32 v60, v0
	v_mov_b32_e32 v61, v0
	v_mov_b32_e32 v62, v0
	v_mov_b32_e32 v63, v0
	v_mov_b32_e32 v64, v0
	v_mov_b32_e32 v65, v0
	v_mov_b32_e32 v66, v0
	v_mov_b32_e32 v67, v0
	v_mov_b32_e32 v68, v0
	v_mov_b32_e32 v69, v0
	v_mov_b32_e32 v70, v0
	v_mov_b32_e32 v71, v0
	v_mov_b32_e32 v72, v0
	v_mov_b32_e32 v73, v0
	v_mov_b32_e32 v74, v0
	v_mov_b32_e32 v75, v0
	v_mov_b32_e32 v76, v0
	v_mov_b32_e32 v77, v0
	v_mov_b32_e32 v78, v0
	v_mov_b32_e32 v79, v0
	v_mov_b32_e32 v80, v0
	v_mov_b32_e32 v81, v0
	v_mov_b32_e32 v82, v0
	v_mov_b32_e32 v83, v0
	v_mov_b32_e32 v84, v0
	v_mov_b32_e32 v85, v0
	v_mov_b32_e32 v86, v0
	v_mov_b32_e32 v87, v0
	v_mov_b32_e32 v88, v0
	v_mov_b32_e32 v89, v0
	v_mov_b32_e32 v90, v0
	v_mov_b32_e32 v91, v0
	v_mov_b32_e32 v92, v0
	v_mov_b32_e32 v93, v0
	v_mov_b32_e32 v94, v0
	v_mov_b32_e32 v95, v0
	v_mov_b32_e32 v96, v0
	v_mov_b32_e32 v97, v0
	v_mov_b32_e32 v98, v0
	v_mov_b32_e32 v99, v0
	v_mov_b32_e32 v100, v0
	v_mov_b32_e32 v101, v0
	v_mov_b32_e32 v102, v0
	v_mov_b32_e32 v103, v0
	v_mov_b32_e32 v104, v0
	v_mov_b32_e32 v105, v0
	v_mov_b32_e32 v106, v0
	v_mov_b32_e32 v107, v0
	v_mov_b32_e32 v108, v0
	v_mov_b32_e32 v109, v0
	v_mov_b32_e32 v110, v0
	v_mov_b32_e32 v111, v0
	v_mov_b32_e32 v112, v0
	v_mov_b32_e32 v113, v0
	v_mov_b32_e32 v114, v0
	v_mov_b32_e32 v115, v0
	v_mov_b32_e32 v116, v0
	v_mov_b32_e32 v117, v0
	v_mov_b32_e32 v118, v0
	v_mov_b32_e32 v119, v0
	v_mov_b32_e32 v120, v0
	v_mov_b32_e32 v121, v0
	v_mov_b32_e32 v122, v0
	v_mov_b32_e32 v123, v0
	v_mov_b32_e32 v124, v0
	v_mov_b32_e32 v125, v0
	v_mov_b32_e32 v126, v0
	v_mov_b32_e32 v127, v0
	s_nop 0

; __global__ void __launch_bounds__(512, 2) mega(Params p) {
;   extern __shared__ __attribute__((aligned(16))) unsigned char smem[];
;   const int wv0 = __builtin_amdgcn_readfirstlane((int)(threadIdx.x >> 6));
	.amdhsa_kernel _Z4mega6Params
		.amdhsa_group_segment_fixed_size 32
		.amdhsa_private_segment_fixed_size 0
		.amdhsa_kernarg_size 472
		.amdhsa_user_sgpr_count 2
		.amdhsa_user_sgpr_dispatch_ptr 0
		.amdhsa_user_sgpr_queue_ptr 0
		.amdhsa_user_sgpr_kernarg_segment_ptr 1
		.amdhsa_user_sgpr_dispatch_id 0
		.amdhsa_user_sgpr_kernarg_preload_length 0
		.amdhsa_user_sgpr_kernarg_preload_offset 0
		.amdhsa_user_sgpr_private_segment_size 0
		.amdhsa_uses_dynamic_stack 0
		.amdhsa_enable_private_segment 0
		.amdhsa_system_sgpr_workgroup_id_x 1
		.amdhsa_system_sgpr_workgroup_id_y 0
		.amdhsa_system_sgpr_workgroup_id_z 0
		.amdhsa_system_sgpr_workgroup_info 0
		.amdhsa_system_vgpr_workitem_id 2
		.amdhsa_next_free_vgpr 256
		.amdhsa_next_free_sgpr 98
		.amdhsa_accum_offset 256
		.amdhsa_reserve_vcc 1
		.amdhsa_float_round_mode_32 0
		.amdhsa_float_round_mode_16_64 0
		.amdhsa_float_denorm_mode_32 3
		.amdhsa_float_denorm_mode_16_64 3
		.amdhsa_dx10_clamp 1
		.amdhsa_ieee_mode 1
		.amdhsa_fp16_overflow 0
		.amdhsa_tg_split 0
		.amdhsa_exception_fp_ieee_invalid_op 0
		.amdhsa_exception_fp_denorm_src 0
		.amdhsa_exception_fp_ieee_div_zero 0
		.amdhsa_exception_fp_ieee_overflow 0
		.amdhsa_exception_fp_ieee_underflow 0
		.amdhsa_exception_fp_ieee_inexact 0
		.amdhsa_exception_int_div_zero 0
	.end_amdhsa_kernel

; __global__ void __launch_bounds__(512, 2) mega(Params p) {
;   extern __shared__ __attribute__((aligned(16))) unsigned char smem[];
;   const int wv0 = __builtin_amdgcn_readfirstlane((int)(threadIdx.x >> 6));
amdhsa.kernels:
  - .agpr_count:     0
    .args:
      - .offset:         0
        .size:           216
        .value_kind:     by_value
      - .offset:         216
        .size:           4
        .value_kind:     hidden_block_count_x
      - .offset:         220
        .size:           4
        .value_kind:     hidden_block_count_y
      - .offset:         224
        .size:           4
        .value_kind:     hidden_block_count_z
      - .offset:         228
        .size:           2
        .value_kind:     hidden_group_size_x
      - .offset:         230
        .size:           2
        .value_kind:     hidden_group_size_y
      - .offset:         232
        .size:           2
        .value_kind:     hidden_group_size_z
      - .offset:         234
        .size:           2
        .value_kind:     hidden_remainder_x
      - .offset:         236
        .size:           2
        .value_kind:     hidden_remainder_y
      - .offset:         238
        .size:           2
        .value_kind:     hidden_remainder_z
      - .offset:         256
        .size:           8
        .value_kind:     hidden_global_offset_x
      - .offset:         264
        .size:           8
        .value_kind:     hidden_global_offset_y
      - .offset:         272
        .size:           8
        .value_kind:     hidden_global_offset_z
      - .offset:         280
        .size:           2
        .value_kind:     hidden_grid_dims
      - .offset:         304
        .size:           8
        .value_kind:     hidden_multigrid_sync_arg
      - .offset:         336
        .size:           4
        .value_kind:     hidden_dynamic_lds_size
    .group_segment_fixed_size: 32
    .kernarg_segment_align: 8
    .kernarg_segment_size: 472
    .language:       OpenCL C
    .language_version:
      - 2
      - 0
    .max_flat_workgroup_size: 512
    .name:           _Z4mega6Params
    .private_segment_fixed_size: 0
    .sgpr_count:     104
    .sgpr_spill_count: 86
    .symbol:         _Z4mega6Params.kd
    .uniform_work_group_size: 1
    .uses_dynamic_stack: false
    .vgpr_count:     256
    .vgpr_spill_count: 0
    .wavefront_size: 64
